# hoisted the two loop-invariant ds_read address adds out of the out/down K-loops into spare VGPRs (no VALU left in any K-loop load segment)
# speedup vs baseline: 1.0004x; 1.0004x over previous
; #define PG8_STAGE(bufoff, gbase, voff) do { _Pragma("unroll") for (int _i = 0; _i < 2; ++_i) \
;         __builtin_amdgcn_global_load_lds((const unsigned*)((const char*)(gbase) + (voff)[_i]), (PG8_LAS unsigned*)(lds + (bufoff) + ldsw + _i * 8192), 16, 0, 0); } while (0)
; #define PG8_LDA(dst, b, h) do { _Pragma("unroll") for (int m = 0; m < 4; ++m) _Pragma("unroll") for (int k = 0; k < 2; ++k) dst[m][k] = *(const PG8_LAS bf16x8*)(lds + PG8_SA(b, h) + aoff + m * 2048 + k * 1024); } while (0)
; #define PG8_LDB(dst, b, h) do { _Pragma("unroll") for (int n = 0; n < 2; ++n) _Pragma("unroll") for (int k = 0; k < 2; ++k) dst[n][k] = *(const PG8_LAS bf16x8*)(lds + PG8_SB(b, h) + boff + n * 2048 + k * 1024); } while (0)
; #define PG8_MMA(ai, bj, At, Bt) do { __builtin_amdgcn_s_setprio(1); _Pragma("unroll") for (int m = 0; m < 4; ++m) _Pragma("unroll") for (int n = 0; n < 2; ++n) _Pragma("unroll") for (int k = 0; k < 2; ++k) \
;         acc[ai][bj][m][n] = __builtin_amdgcn_mfma_f32_16x16x32_bf16(Bt[n][k], At[m][k], acc[ai][bj][m][n], 0, 0, 0); __builtin_amdgcn_s_setprio(0); } while (0)
; #define PG8_WAIT_V(n) asm volatile("s_waitcnt vmcnt(" #n ")" ::: "memory")
; #define PG8_WAIT_L(n) asm volatile("s_waitcnt lgkmcnt(" #n ")" ::: "memory")
; #define PG8_BAR __builtin_amdgcn_s_barrier()
; #define PG8_SCHED __builtin_amdgcn_sched_barrier(0)
; template <class Epi, class Sched, bool ALIGN_EPI = false, bool SP2 = false>
; __device__ __forceinline__ void gemm_phase(PG8_LAS unsigned char* lds, const Gemm g, const Sched& S, const Epi& E, int wave_s) {
;     ...
;             PG8_LDB(B0, 0, 0); PG8_LDB(B1, 0, 1); PG8_SCHED; PG8_LDA(At, 0, 0); PG8_STAGE(PG8_SA(1, 1), a1 + hstep, voffA);
;             PG8_WAIT_V(8); PG8_WAIT_L(0); PG8_BAR; PG8_MMA(0, 0, At, B0); PG8_MMA(0, 1, At, B1); PG8_BAR; PG8_SCHED;
;     ...
;         for (int a = 0; a < 2; ++a)
; #pragma unroll
;             for (int b = 0; b < 2; ++b)
; #pragma unroll
;                 for (int m = 0; m < 4; ++m)
; #pragma unroll
;                     for (int n = 0; n < 2; ++n) acc[a][b][m][n] = (f32x4){0.f, 0.f, 0.f, 0.f};
;         cur = nxt; cA = nA; cB = nB; ++ui;
.LBB0_1199:
	s_add_u32 s50, s50, 0x100080
	s_addc_u32 s51, s51, 0
	s_add_u32 s7, s52, 0x100
	v_mov_b32_e32 v0, 0
	s_addc_u32 s41, s53, 0
	s_mov_b32 s43, 2
	s_waitcnt lgkmcnt(0)
	v_mov_b32_e32 v1, v0
	v_mov_b32_e32 v2, v0
	v_mov_b32_e32 v3, v0
	v_mov_b32_e32 v4, v0
	v_mov_b32_e32 v5, v0
	v_mov_b32_e32 v6, v0
	v_mov_b32_e32 v7, v0
	v_mov_b32_e32 v16, v0
	v_mov_b32_e32 v17, v0
	v_mov_b32_e32 v18, v0
	v_mov_b32_e32 v19, v0
	v_mov_b32_e32 v20, v0
	v_mov_b32_e32 v21, v0
	v_mov_b32_e32 v22, v0
	v_mov_b32_e32 v23, v0
	v_mov_b32_e32 v32, v0
	v_mov_b32_e32 v33, v0
	v_mov_b32_e32 v34, v0
	v_mov_b32_e32 v35, v0
	v_mov_b32_e32 v36, v0
	v_mov_b32_e32 v37, v0
	v_mov_b32_e32 v38, v0
	v_mov_b32_e32 v39, v0
	v_mov_b32_e32 v48, v0
	v_mov_b32_e32 v49, v0
	v_mov_b32_e32 v50, v0
	v_mov_b32_e32 v51, v0
	v_mov_b32_e32 v52, v0
	v_mov_b32_e32 v53, v0
	v_mov_b32_e32 v54, v0
	v_mov_b32_e32 v55, v0
	v_mov_b32_e32 v8, v0
	v_mov_b32_e32 v9, v0
	v_mov_b32_e32 v10, v0
	v_mov_b32_e32 v11, v0
	v_mov_b32_e32 v12, v0
	v_mov_b32_e32 v13, v0
	v_mov_b32_e32 v14, v0
	v_mov_b32_e32 v15, v0
	v_mov_b32_e32 v24, v0
	v_mov_b32_e32 v25, v0
	v_mov_b32_e32 v26, v0
	v_mov_b32_e32 v27, v0
	v_mov_b32_e32 v28, v0
	v_mov_b32_e32 v29, v0
	v_mov_b32_e32 v30, v0
	v_mov_b32_e32 v31, v0
	v_mov_b32_e32 v40, v0
	v_mov_b32_e32 v41, v0
	v_mov_b32_e32 v42, v0
	v_mov_b32_e32 v43, v0
	v_mov_b32_e32 v44, v0
	v_mov_b32_e32 v45, v0
	v_mov_b32_e32 v46, v0
	v_mov_b32_e32 v47, v0
	v_mov_b32_e32 v56, v0
	v_mov_b32_e32 v57, v0
	v_mov_b32_e32 v58, v0
	v_mov_b32_e32 v59, v0
	v_mov_b32_e32 v60, v0
	v_mov_b32_e32 v61, v0
	v_mov_b32_e32 v62, v0
	v_mov_b32_e32 v63, v0
	v_mov_b32_e32 v64, v0
	v_mov_b32_e32 v65, v0
	v_mov_b32_e32 v66, v0
	v_mov_b32_e32 v67, v0
	v_mov_b32_e32 v68, v0
	v_mov_b32_e32 v69, v0
	v_mov_b32_e32 v70, v0
	v_mov_b32_e32 v71, v0
	v_mov_b32_e32 v80, v0
	v_mov_b32_e32 v81, v0
	v_mov_b32_e32 v82, v0
	v_mov_b32_e32 v83, v0
	v_mov_b32_e32 v84, v0
	v_mov_b32_e32 v85, v0
	v_mov_b32_e32 v86, v0
	v_mov_b32_e32 v87, v0
	v_mov_b32_e32 v96, v0
	v_mov_b32_e32 v97, v0
	v_mov_b32_e32 v98, v0
	v_mov_b32_e32 v99, v0
	v_mov_b32_e32 v100, v0
	v_mov_b32_e32 v101, v0
	v_mov_b32_e32 v102, v0
	v_mov_b32_e32 v103, v0
	v_mov_b32_e32 v112, v0
	v_mov_b32_e32 v113, v0
	v_mov_b32_e32 v114, v0
	v_mov_b32_e32 v115, v0
	v_mov_b32_e32 v116, v0
	v_mov_b32_e32 v117, v0
	v_mov_b32_e32 v118, v0
	v_mov_b32_e32 v119, v0
	v_mov_b32_e32 v72, v0
	v_mov_b32_e32 v73, v0
	v_mov_b32_e32 v74, v0
	v_mov_b32_e32 v75, v0
	v_mov_b32_e32 v76, v0
	v_mov_b32_e32 v77, v0
	v_mov_b32_e32 v78, v0
	v_mov_b32_e32 v79, v0
	v_mov_b32_e32 v88, v0
	v_mov_b32_e32 v89, v0
	v_mov_b32_e32 v90, v0
	v_mov_b32_e32 v91, v0
	v_mov_b32_e32 v92, v0
	v_mov_b32_e32 v93, v0
	v_mov_b32_e32 v94, v0
	v_mov_b32_e32 v95, v0
	v_mov_b32_e32 v104, v0
	v_mov_b32_e32 v105, v0
	v_mov_b32_e32 v106, v0
	v_mov_b32_e32 v107, v0
	v_mov_b32_e32 v108, v0
	v_mov_b32_e32 v109, v0
	v_mov_b32_e32 v110, v0
	v_mov_b32_e32 v111, v0
	v_mov_b32_e32 v120, v0
	v_mov_b32_e32 v121, v0
	v_mov_b32_e32 v122, v0
	v_mov_b32_e32 v123, v0
	v_mov_b32_e32 v124, v0
	v_mov_b32_e32 v125, v0
	v_mov_b32_e32 v126, v0
	v_mov_b32_e32 v127, v0
	v_add_u32_e32 v230, 0x18000, v210
	v_add_u32_e32 v231, 0x1c000, v210
.LBB0_1200:
	ds_read_b128 v[128:131], v211
	ds_read_b128 v[132:135], v211 offset:1024
	ds_read_b128 v[136:139], v211 offset:2048
	ds_read_b128 v[140:143], v211 offset:3072
	ds_read_b128 v[144:147], v212
	ds_read_b128 v[148:151], v212 offset:1024
	ds_read_b128 v[152:155], v212 offset:2048
	ds_read_b128 v[156:159], v212 offset:3072
	s_add_u32 s45, s50, 0xfff00080
	s_addc_u32 s52, s51, -1
	s_cmp_eq_u32 s85, s43
	s_cselect_b32 s55, s47, s52
	s_cselect_b32 s54, s46, s45
	s_cselect_b32 s53, s49, s41
	s_cselect_b32 s52, s48, s7
	s_add_i32 m0, s9, 0xc000
	ds_read_b128 v[160:163], v213
	ds_read_b128 v[164:167], v213 offset:1024
	ds_read_b128 v[168:171], v213 offset:2048
	ds_read_b128 v[172:175], v213 offset:3072
	ds_read_b128 v[176:179], v213 offset:4096
	ds_read_b128 v[180:183], v213 offset:5120
	ds_read_b128 v[196:199], v213 offset:6144
	ds_read_b128 v[200:203], v213 offset:7168
	global_load_lds_dwordx4 v192, s[50:51]
	s_add_i32 m0, s9, 0xe000
	s_nop 0
	global_load_lds_dwordx4 v194, s[50:51]
	s_waitcnt vmcnt(8)
	s_waitcnt lgkmcnt(0)
	s_barrier
	v_mfma_f32_16x16x32_bf16 v[124:127], v[128:131], v[160:163], v[124:127]
	v_mfma_f32_16x16x32_bf16 v[124:127], v[132:135], v[164:167], v[124:127]
	v_mfma_f32_16x16x32_bf16 v[120:123], v[140:143], v[164:167], v[120:123]
	v_mfma_f32_16x16x32_bf16 v[120:123], v[136:139], v[160:163], v[120:123]
	v_mfma_f32_16x16x32_bf16 v[104:107], v[136:139], v[168:171], v[104:107]
	v_mfma_f32_16x16x32_bf16 v[104:107], v[140:143], v[172:175], v[104:107]
	v_mfma_f32_16x16x32_bf16 v[108:111], v[132:135], v[172:175], v[108:111]
	v_mfma_f32_16x16x32_bf16 v[108:111], v[128:131], v[168:171], v[108:111]
	v_mfma_f32_16x16x32_bf16 v[92:95], v[128:131], v[176:179], v[92:95]
	v_mfma_f32_16x16x32_bf16 v[92:95], v[132:135], v[180:183], v[92:95]
	v_mfma_f32_16x16x32_bf16 v[88:91], v[140:143], v[180:183], v[88:91]
	v_mfma_f32_16x16x32_bf16 v[88:91], v[136:139], v[176:179], v[88:91]
	v_mfma_f32_16x16x32_bf16 v[72:75], v[136:139], v[196:199], v[72:75]
	v_mfma_f32_16x16x32_bf16 v[72:75], v[140:143], v[200:203], v[72:75]
	v_mfma_f32_16x16x32_bf16 v[76:79], v[132:135], v[200:203], v[76:79]
	v_mfma_f32_16x16x32_bf16 v[76:79], v[128:131], v[196:199], v[76:79]
	v_mfma_f32_16x16x32_bf16 v[116:119], v[144:147], v[160:163], v[116:119]
	v_mfma_f32_16x16x32_bf16 v[116:119], v[148:151], v[164:167], v[116:119]
	v_mfma_f32_16x16x32_bf16 v[112:115], v[156:159], v[164:167], v[112:115]
	v_mfma_f32_16x16x32_bf16 v[112:115], v[152:155], v[160:163], v[112:115]
	v_mfma_f32_16x16x32_bf16 v[96:99], v[152:155], v[168:171], v[96:99]
	v_mfma_f32_16x16x32_bf16 v[96:99], v[156:159], v[172:175], v[96:99]
	v_mfma_f32_16x16x32_bf16 v[100:103], v[148:151], v[172:175], v[100:103]
	v_mfma_f32_16x16x32_bf16 v[100:103], v[144:147], v[168:171], v[100:103]
	v_mfma_f32_16x16x32_bf16 v[84:87], v[144:147], v[176:179], v[84:87]
	v_mfma_f32_16x16x32_bf16 v[84:87], v[148:151], v[180:183], v[84:87]
	v_mfma_f32_16x16x32_bf16 v[80:83], v[156:159], v[180:183], v[80:83]
	v_mfma_f32_16x16x32_bf16 v[80:83], v[152:155], v[176:179], v[80:83]
	v_mfma_f32_16x16x32_bf16 v[64:67], v[152:155], v[196:199], v[64:67]
	v_mfma_f32_16x16x32_bf16 v[64:67], v[156:159], v[200:203], v[64:67]
	v_mfma_f32_16x16x32_bf16 v[68:71], v[148:151], v[200:203], v[68:71]
	v_mfma_f32_16x16x32_bf16 v[68:71], v[144:147], v[196:199], v[68:71]
	s_barrier
; #define PG8_STAGE(bufoff, gbase, voff) do { _Pragma("unroll") for (int _i = 0; _i < 2; ++_i) \
;         __builtin_amdgcn_global_load_lds((const unsigned*)((const char*)(gbase) + (voff)[_i]), (PG8_LAS unsigned*)(lds + (bufoff) + ldsw + _i * 8192), 16, 0, 0); } while (0)
; #define PG8_LDA(dst, b, h) do { _Pragma("unroll") for (int m = 0; m < 4; ++m) _Pragma("unroll") for (int k = 0; k < 2; ++k) dst[m][k] = *(const PG8_LAS bf16x8*)(lds + PG8_SA(b, h) + aoff + m * 2048 + k * 1024); } while (0)
; #define PG8_LDB(dst, b, h) do { _Pragma("unroll") for (int n = 0; n < 2; ++n) _Pragma("unroll") for (int k = 0; k < 2; ++k) dst[n][k] = *(const PG8_LAS bf16x8*)(lds + PG8_SB(b, h) + boff + n * 2048 + k * 1024); } while (0)
; #define PG8_MMA(ai, bj, At, Bt) do { __builtin_amdgcn_s_setprio(1); _Pragma("unroll") for (int m = 0; m < 4; ++m) _Pragma("unroll") for (int n = 0; n < 2; ++n) _Pragma("unroll") for (int k = 0; k < 2; ++k) \
;         acc[ai][bj][m][n] = __builtin_amdgcn_mfma_f32_16x16x32_bf16(Bt[n][k], At[m][k], acc[ai][bj][m][n], 0, 0, 0); __builtin_amdgcn_s_setprio(0); } while (0)
; #define PG8_WAIT_V(n) asm volatile("s_waitcnt vmcnt(" #n ")" ::: "memory")
; #define PG8_WAIT_L(n) asm volatile("s_waitcnt lgkmcnt(" #n ")" ::: "memory")
; #define PG8_BAR __builtin_amdgcn_s_barrier()
; #define PG8_SCHED __builtin_amdgcn_sched_barrier(0)
; template <class Epi, class Sched, bool ALIGN_EPI = false, bool SP2 = false>
; __device__ __forceinline__ void gemm_phase(PG8_LAS unsigned char* lds, const Gemm g, const Sched& S, const Epi& E, int wave_s) {
;     ...
;             PG8_LDA(At, 0, 1); PG8_STAGE(PG8_SB(0, 0), b2, voffB); PG8_STAGE(PG8_SB(0, 1), b2 + hstep, voffB); PG8_STAGE(PG8_SA(0, 0), a2, voffA);
;             PG8_WAIT_V(8); PG8_WAIT_L(0); PG8_BAR; PG8_MMA(1, 0, At, B0); PG8_MMA(1, 1, At, B1); PG8_BAR; PG8_SCHED;
;             PG8_LDB(B0, 1, 0); PG8_LDB(B1, 1, 1); PG8_SCHED; PG8_LDA(At, 1, 0); PG8_STAGE(PG8_SA(0, 1), a2 + hstep, voffA);
;             PG8_WAIT_V(8); PG8_WAIT_L(0); PG8_BAR; PG8_MMA(0, 0, At, B0); PG8_MMA(0, 1, At, B1); PG8_BAR; PG8_SCHED;
	s_add_i32 s45, s75, s60
	s_mov_b32 m0, s45
	ds_read_b128 v[160:163], v213 offset:16384
	ds_read_b128 v[164:167], v213 offset:17408
	ds_read_b128 v[168:171], v213 offset:18432
	ds_read_b128 v[172:175], v213 offset:19456
	ds_read_b128 v[176:179], v213 offset:20480
	ds_read_b128 v[180:183], v213 offset:21504
	ds_read_b128 v[196:199], v213 offset:22528
	ds_read_b128 v[200:203], v213 offset:23552
	global_load_lds_dwordx4 v186, s[52:53]
	s_add_i32 m0, s45, 0x2000
	s_add_u32 s86, s52, 0x100000
	s_addc_u32 s87, s53, 0
	s_add_i32 s45, s76, s60
	global_load_lds_dwordx4 v190, s[52:53]
	s_mov_b32 m0, s45
	s_nop 0
	global_load_lds_dwordx4 v186, s[86:87]
	s_add_i32 m0, s45, 0x2000
	s_nop 0
	global_load_lds_dwordx4 v190, s[86:87]
	s_mov_b32 m0, s9
	s_nop 0
	global_load_lds_dwordx4 v184, s[54:55]
	s_mov_b32 m0, s61
	s_nop 0
	global_load_lds_dwordx4 v188, s[54:55]
	s_waitcnt vmcnt(8)
	s_waitcnt lgkmcnt(0)
	s_barrier
	v_mfma_f32_16x16x32_bf16 v[60:63], v[128:131], v[160:163], v[60:63]
	v_mfma_f32_16x16x32_bf16 v[60:63], v[132:135], v[164:167], v[60:63]
	v_mfma_f32_16x16x32_bf16 v[56:59], v[140:143], v[164:167], v[56:59]
	v_mfma_f32_16x16x32_bf16 v[56:59], v[136:139], v[160:163], v[56:59]
	v_mfma_f32_16x16x32_bf16 v[40:43], v[136:139], v[168:171], v[40:43]
	v_mfma_f32_16x16x32_bf16 v[40:43], v[140:143], v[172:175], v[40:43]
	v_mfma_f32_16x16x32_bf16 v[44:47], v[132:135], v[172:175], v[44:47]
	v_mfma_f32_16x16x32_bf16 v[44:47], v[128:131], v[168:171], v[44:47]
	v_mfma_f32_16x16x32_bf16 v[28:31], v[128:131], v[176:179], v[28:31]
	v_mfma_f32_16x16x32_bf16 v[28:31], v[132:135], v[180:183], v[28:31]
	v_mfma_f32_16x16x32_bf16 v[24:27], v[140:143], v[180:183], v[24:27]
	v_mfma_f32_16x16x32_bf16 v[24:27], v[136:139], v[176:179], v[24:27]
	v_mfma_f32_16x16x32_bf16 v[8:11], v[136:139], v[196:199], v[8:11]
	v_mfma_f32_16x16x32_bf16 v[8:11], v[140:143], v[200:203], v[8:11]
	v_mfma_f32_16x16x32_bf16 v[12:15], v[132:135], v[200:203], v[12:15]
	v_mfma_f32_16x16x32_bf16 v[12:15], v[128:131], v[196:199], v[12:15]
	v_mfma_f32_16x16x32_bf16 v[52:55], v[144:147], v[160:163], v[52:55]
	v_mfma_f32_16x16x32_bf16 v[52:55], v[148:151], v[164:167], v[52:55]
	v_mfma_f32_16x16x32_bf16 v[48:51], v[156:159], v[164:167], v[48:51]
	v_mfma_f32_16x16x32_bf16 v[48:51], v[152:155], v[160:163], v[48:51]
	v_mfma_f32_16x16x32_bf16 v[32:35], v[152:155], v[168:171], v[32:35]
	v_mfma_f32_16x16x32_bf16 v[32:35], v[156:159], v[172:175], v[32:35]
	v_mfma_f32_16x16x32_bf16 v[36:39], v[148:151], v[172:175], v[36:39]
	v_mfma_f32_16x16x32_bf16 v[36:39], v[144:147], v[168:171], v[36:39]
	v_mfma_f32_16x16x32_bf16 v[20:23], v[144:147], v[176:179], v[20:23]
	v_mfma_f32_16x16x32_bf16 v[20:23], v[148:151], v[180:183], v[20:23]
	v_mfma_f32_16x16x32_bf16 v[16:19], v[156:159], v[180:183], v[16:19]
	v_mfma_f32_16x16x32_bf16 v[16:19], v[152:155], v[176:179], v[16:19]
	v_mfma_f32_16x16x32_bf16 v[0:3], v[152:155], v[196:199], v[0:3]
	v_mfma_f32_16x16x32_bf16 v[0:3], v[156:159], v[200:203], v[0:3]
	v_mfma_f32_16x16x32_bf16 v[4:7], v[148:151], v[200:203], v[4:7]
	v_mfma_f32_16x16x32_bf16 v[4:7], v[144:147], v[196:199], v[4:7]
	s_barrier
	s_add_i32 s45, 0, 0x18000
	s_add_i32 s86, 0, 0x1c000
	ds_read_b128 v[128:131], v230
	ds_read_b128 v[132:135], v230 offset:1024
	ds_read_b128 v[136:139], v230 offset:2048
	ds_read_b128 v[140:143], v230 offset:3072
	ds_read_b128 v[144:147], v231
	ds_read_b128 v[148:151], v231 offset:1024
	ds_read_b128 v[152:155], v231 offset:2048
	ds_read_b128 v[156:159], v231 offset:3072
	s_add_u32 s54, s54, 0x100000
	s_addc_u32 s55, s55, 0
	s_mov_b32 m0, s62
	s_nop 0
	ds_read_b128 v[160:163], v213 offset:32768
	ds_read_b128 v[164:167], v213 offset:33792
	ds_read_b128 v[168:171], v213 offset:34816
	ds_read_b128 v[172:175], v213 offset:35840
	ds_read_b128 v[176:179], v213 offset:36864
	ds_read_b128 v[180:183], v213 offset:37888
	ds_read_b128 v[196:199], v213 offset:38912
	ds_read_b128 v[200:203], v213 offset:39936
	global_load_lds_dwordx4 v184, s[54:55]
	s_mov_b32 m0, s63
	s_nop 0
	global_load_lds_dwordx4 v188, s[54:55]
	s_waitcnt vmcnt(8)
	s_waitcnt lgkmcnt(0)
	s_barrier
; #define PG8_STAGE(bufoff, gbase, voff) do { _Pragma("unroll") for (int _i = 0; _i < 2; ++_i) \
;         __builtin_amdgcn_global_load_lds((const unsigned*)((const char*)(gbase) + (voff)[_i]), (PG8_LAS unsigned*)(lds + (bufoff) + ldsw + _i * 8192), 16, 0, 0); } while (0)
; #define PG8_LDA(dst, b, h) do { _Pragma("unroll") for (int m = 0; m < 4; ++m) _Pragma("unroll") for (int k = 0; k < 2; ++k) dst[m][k] = *(const PG8_LAS bf16x8*)(lds + PG8_SA(b, h) + aoff + m * 2048 + k * 1024); } while (0)
; #define PG8_MMA(ai, bj, At, Bt) do { __builtin_amdgcn_s_setprio(1); _Pragma("unroll") for (int m = 0; m < 4; ++m) _Pragma("unroll") for (int n = 0; n < 2; ++n) _Pragma("unroll") for (int k = 0; k < 2; ++k) \
;         acc[ai][bj][m][n] = __builtin_amdgcn_mfma_f32_16x16x32_bf16(Bt[n][k], At[m][k], acc[ai][bj][m][n], 0, 0, 0); __builtin_amdgcn_s_setprio(0); } while (0)
; #define PG8_WAIT_V(n) asm volatile("s_waitcnt vmcnt(" #n ")" ::: "memory")
; #define PG8_WAIT_L(n) asm volatile("s_waitcnt lgkmcnt(" #n ")" ::: "memory")
; #define PG8_BAR __builtin_amdgcn_s_barrier()
; #define PG8_SCHED __builtin_amdgcn_sched_barrier(0)
; template <class Epi, class Sched, bool ALIGN_EPI = false, bool SP2 = false>
; __device__ __forceinline__ void gemm_phase(PG8_LAS unsigned char* lds, const Gemm g, const Sched& S, const Epi& E, int wave_s) {
;     ...
;             PG8_WAIT_V(8); PG8_WAIT_L(0); PG8_BAR; PG8_MMA(0, 0, At, B0); PG8_MMA(0, 1, At, B1); PG8_BAR; PG8_SCHED;
;             PG8_LDA(At, 1, 1); PG8_STAGE(PG8_SB(1, 0), b3, voffB); PG8_STAGE(PG8_SB(1, 1), b3 + hstep, voffB); PG8_STAGE(PG8_SA(1, 0), a3, voffA);
;             PG8_WAIT_V(8); PG8_WAIT_L(0); PG8_BAR; PG8_MMA(1, 0, At, B0); PG8_MMA(1, 1, At, B1); PG8_BAR; PG8_SCHED;
	v_mfma_f32_16x16x32_bf16 v[124:127], v[128:131], v[160:163], v[124:127]
	v_mfma_f32_16x16x32_bf16 v[124:127], v[132:135], v[164:167], v[124:127]
	v_mfma_f32_16x16x32_bf16 v[120:123], v[140:143], v[164:167], v[120:123]
	v_mfma_f32_16x16x32_bf16 v[120:123], v[136:139], v[160:163], v[120:123]
	v_mfma_f32_16x16x32_bf16 v[104:107], v[136:139], v[168:171], v[104:107]
	v_mfma_f32_16x16x32_bf16 v[104:107], v[140:143], v[172:175], v[104:107]
	v_mfma_f32_16x16x32_bf16 v[108:111], v[132:135], v[172:175], v[108:111]
	v_mfma_f32_16x16x32_bf16 v[108:111], v[128:131], v[168:171], v[108:111]
	v_mfma_f32_16x16x32_bf16 v[92:95], v[128:131], v[176:179], v[92:95]
	v_mfma_f32_16x16x32_bf16 v[92:95], v[132:135], v[180:183], v[92:95]
	v_mfma_f32_16x16x32_bf16 v[88:91], v[140:143], v[180:183], v[88:91]
	v_mfma_f32_16x16x32_bf16 v[88:91], v[136:139], v[176:179], v[88:91]
	v_mfma_f32_16x16x32_bf16 v[72:75], v[136:139], v[196:199], v[72:75]
	v_mfma_f32_16x16x32_bf16 v[72:75], v[140:143], v[200:203], v[72:75]
	v_mfma_f32_16x16x32_bf16 v[76:79], v[132:135], v[200:203], v[76:79]
	v_mfma_f32_16x16x32_bf16 v[76:79], v[128:131], v[196:199], v[76:79]
	v_mfma_f32_16x16x32_bf16 v[116:119], v[144:147], v[160:163], v[116:119]
	v_mfma_f32_16x16x32_bf16 v[116:119], v[148:151], v[164:167], v[116:119]
	v_mfma_f32_16x16x32_bf16 v[112:115], v[156:159], v[164:167], v[112:115]
	v_mfma_f32_16x16x32_bf16 v[112:115], v[152:155], v[160:163], v[112:115]
	v_mfma_f32_16x16x32_bf16 v[96:99], v[152:155], v[168:171], v[96:99]
	v_mfma_f32_16x16x32_bf16 v[96:99], v[156:159], v[172:175], v[96:99]
	v_mfma_f32_16x16x32_bf16 v[100:103], v[148:151], v[172:175], v[100:103]
	v_mfma_f32_16x16x32_bf16 v[100:103], v[144:147], v[168:171], v[100:103]
	v_mfma_f32_16x16x32_bf16 v[84:87], v[144:147], v[176:179], v[84:87]
	v_mfma_f32_16x16x32_bf16 v[84:87], v[148:151], v[180:183], v[84:87]
	v_mfma_f32_16x16x32_bf16 v[80:83], v[156:159], v[180:183], v[80:83]
	v_mfma_f32_16x16x32_bf16 v[80:83], v[152:155], v[176:179], v[80:83]
	v_mfma_f32_16x16x32_bf16 v[64:67], v[152:155], v[196:199], v[64:67]
	v_mfma_f32_16x16x32_bf16 v[64:67], v[156:159], v[200:203], v[64:67]
	v_mfma_f32_16x16x32_bf16 v[68:71], v[148:151], v[200:203], v[68:71]
	v_mfma_f32_16x16x32_bf16 v[68:71], v[144:147], v[196:199], v[68:71]
	s_barrier
	s_add_i32 s45, s45, s60
	s_mov_b32 m0, s45
	ds_read_b128 v[160:163], v213 offset:49152
	ds_read_b128 v[164:167], v213 offset:50176
	ds_read_b128 v[168:171], v213 offset:51200
	ds_read_b128 v[172:175], v213 offset:52224
	ds_read_b128 v[176:179], v213 offset:53248
	ds_read_b128 v[180:183], v213 offset:54272
	ds_read_b128 v[196:199], v213 offset:55296
	ds_read_b128 v[200:203], v213 offset:56320
	s_add_u32 s94, s52, 0x80
	s_addc_u32 s95, s53, 0
	global_load_lds_dwordx4 v186, s[94:95]
	s_add_i32 m0, s45, 0x2000
	s_add_u32 s52, s52, 0x100080
	s_addc_u32 s53, s53, 0
	s_add_i32 s45, s86, s60
	global_load_lds_dwordx4 v190, s[94:95]
	s_mov_b32 m0, s45
	s_nop 0
	global_load_lds_dwordx4 v186, s[52:53]
	s_add_i32 m0, s45, 0x2000
	s_nop 0
	global_load_lds_dwordx4 v190, s[52:53]
	s_mov_b32 m0, s70
	s_nop 0
	s_add_u32 s96, s54, 0xfff00080
	s_addc_u32 s97, s55, -1
	global_load_lds_dwordx4 v184, s[96:97]
	s_mov_b32 m0, s71
	s_nop 0
	global_load_lds_dwordx4 v188, s[96:97]
	s_waitcnt vmcnt(8)
	s_waitcnt lgkmcnt(0)
	s_barrier
	v_mfma_f32_16x16x32_bf16 v[60:63], v[128:131], v[160:163], v[60:63]
	v_mfma_f32_16x16x32_bf16 v[60:63], v[132:135], v[164:167], v[60:63]
	v_mfma_f32_16x16x32_bf16 v[56:59], v[140:143], v[164:167], v[56:59]
	v_mfma_f32_16x16x32_bf16 v[56:59], v[136:139], v[160:163], v[56:59]
	v_mfma_f32_16x16x32_bf16 v[40:43], v[136:139], v[168:171], v[40:43]
	v_mfma_f32_16x16x32_bf16 v[40:43], v[140:143], v[172:175], v[40:43]
	v_mfma_f32_16x16x32_bf16 v[44:47], v[132:135], v[172:175], v[44:47]
	v_mfma_f32_16x16x32_bf16 v[44:47], v[128:131], v[168:171], v[44:47]
	v_mfma_f32_16x16x32_bf16 v[28:31], v[128:131], v[176:179], v[28:31]
	v_mfma_f32_16x16x32_bf16 v[28:31], v[132:135], v[180:183], v[28:31]
	v_mfma_f32_16x16x32_bf16 v[24:27], v[140:143], v[180:183], v[24:27]
	v_mfma_f32_16x16x32_bf16 v[24:27], v[136:139], v[176:179], v[24:27]
	v_mfma_f32_16x16x32_bf16 v[8:11], v[136:139], v[196:199], v[8:11]
	v_mfma_f32_16x16x32_bf16 v[8:11], v[140:143], v[200:203], v[8:11]
	v_mfma_f32_16x16x32_bf16 v[12:15], v[132:135], v[200:203], v[12:15]
	v_mfma_f32_16x16x32_bf16 v[12:15], v[128:131], v[196:199], v[12:15]
	v_mfma_f32_16x16x32_bf16 v[52:55], v[144:147], v[160:163], v[52:55]
	v_mfma_f32_16x16x32_bf16 v[52:55], v[148:151], v[164:167], v[52:55]
	v_mfma_f32_16x16x32_bf16 v[48:51], v[156:159], v[164:167], v[48:51]
	v_mfma_f32_16x16x32_bf16 v[48:51], v[152:155], v[160:163], v[48:51]
	v_mfma_f32_16x16x32_bf16 v[32:35], v[152:155], v[168:171], v[32:35]
	v_mfma_f32_16x16x32_bf16 v[32:35], v[156:159], v[172:175], v[32:35]
	v_mfma_f32_16x16x32_bf16 v[36:39], v[148:151], v[172:175], v[36:39]
	v_mfma_f32_16x16x32_bf16 v[36:39], v[144:147], v[168:171], v[36:39]
	v_mfma_f32_16x16x32_bf16 v[20:23], v[144:147], v[176:179], v[20:23]
	v_mfma_f32_16x16x32_bf16 v[20:23], v[148:151], v[180:183], v[20:23]
	v_mfma_f32_16x16x32_bf16 v[16:19], v[156:159], v[180:183], v[16:19]
	v_mfma_f32_16x16x32_bf16 v[16:19], v[152:155], v[176:179], v[16:19]
	v_mfma_f32_16x16x32_bf16 v[0:3], v[152:155], v[196:199], v[0:3]
	v_mfma_f32_16x16x32_bf16 v[0:3], v[156:159], v[200:203], v[0:3]
	v_mfma_f32_16x16x32_bf16 v[4:7], v[148:151], v[200:203], v[4:7]
	v_mfma_f32_16x16x32_bf16 v[4:7], v[144:147], v[196:199], v[4:7]
	s_barrier
	s_add_i32 s45, s43, 2
	s_add_u32 s50, s50, 0x100
	s_addc_u32 s51, s51, 0
	s_add_u32 s7, s7, 0x100
	s_addc_u32 s41, s41, 0
	s_cmp_ge_i32 s43, s85
	s_mov_b32 s43, s45
	s_cbranch_scc0 .LBB0_1200
	s_and_b64 vcc, exec, s[20:21]
	s_cbranch_vccz .LBB0_1203
	s_barrier

; #define PG8_STAGE(bufoff, gbase, voff) do { _Pragma("unroll") for (int _i = 0; _i < 2; ++_i) \
;         __builtin_amdgcn_global_load_lds((const unsigned*)((const char*)(gbase) + (voff)[_i]), (PG8_LAS unsigned*)(lds + (bufoff) + ldsw + _i * 8192), 16, 0, 0); } while (0)
; #define PG8_LDA(dst, b, h) do { _Pragma("unroll") for (int m = 0; m < 4; ++m) _Pragma("unroll") for (int k = 0; k < 2; ++k) dst[m][k] = *(const PG8_LAS bf16x8*)(lds + PG8_SA(b, h) + aoff + m * 2048 + k * 1024); } while (0)
; #define PG8_LDB(dst, b, h) do { _Pragma("unroll") for (int n = 0; n < 2; ++n) _Pragma("unroll") for (int k = 0; k < 2; ++k) dst[n][k] = *(const PG8_LAS bf16x8*)(lds + PG8_SB(b, h) + boff + n * 2048 + k * 1024); } while (0)
; #define PG8_MMA(ai, bj, At, Bt) do { __builtin_amdgcn_s_setprio(1); _Pragma("unroll") for (int m = 0; m < 4; ++m) _Pragma("unroll") for (int n = 0; n < 2; ++n) _Pragma("unroll") for (int k = 0; k < 2; ++k) \
;         acc[ai][bj][m][n] = __builtin_amdgcn_mfma_f32_16x16x32_bf16(Bt[n][k], At[m][k], acc[ai][bj][m][n], 0, 0, 0); __builtin_amdgcn_s_setprio(0); } while (0)
; #define PG8_WAIT_V(n) asm volatile("s_waitcnt vmcnt(" #n ")" ::: "memory")
; #define PG8_WAIT_L(n) asm volatile("s_waitcnt lgkmcnt(" #n ")" ::: "memory")
; #define PG8_BAR __builtin_amdgcn_s_barrier()
; #define PG8_SCHED __builtin_amdgcn_sched_barrier(0)
; template <class Epi, class Sched, bool ALIGN_EPI = false, bool SP2 = false>
; __device__ __forceinline__ void gemm_phase(PG8_LAS unsigned char* lds, const Gemm g, const Sched& S, const Epi& E, int wave_s) {
;     ...
;             PG8_LDB(B0, 0, 0); PG8_LDB(B1, 0, 1); PG8_SCHED; PG8_LDA(At, 0, 0); PG8_STAGE(PG8_SA(1, 1), a1 + hstep, voffA);
;             PG8_WAIT_V(8); PG8_WAIT_L(0); PG8_BAR; PG8_MMA(0, 0, At, B0); PG8_MMA(0, 1, At, B1); PG8_BAR; PG8_SCHED;
;     ...
;         for (int a = 0; a < 2; ++a)
; #pragma unroll
;             for (int b = 0; b < 2; ++b)
; #pragma unroll
;                 for (int m = 0; m < 4; ++m)
; #pragma unroll
;                     for (int n = 0; n < 2; ++n) acc[a][b][m][n] = (f32x4){0.f, 0.f, 0.f, 0.f};
;         cur = nxt; cA = nA; cB = nB; ++ui;
.LBB0_1409:
	s_add_u32 s50, s50, 0x400080
	s_addc_u32 s51, s51, 0
	s_add_u32 s7, s52, 0x100
	v_mov_b32_e32 v0, 0
	s_addc_u32 s41, s53, 0
	s_mov_b32 s43, 2
	s_waitcnt lgkmcnt(0)
	v_mov_b32_e32 v1, v0
	v_mov_b32_e32 v2, v0
	v_mov_b32_e32 v3, v0
	v_mov_b32_e32 v4, v0
	v_mov_b32_e32 v5, v0
	v_mov_b32_e32 v6, v0
	v_mov_b32_e32 v7, v0
	v_mov_b32_e32 v16, v0
	v_mov_b32_e32 v17, v0
	v_mov_b32_e32 v18, v0
	v_mov_b32_e32 v19, v0
	v_mov_b32_e32 v20, v0
	v_mov_b32_e32 v21, v0
	v_mov_b32_e32 v22, v0
	v_mov_b32_e32 v23, v0
	v_mov_b32_e32 v32, v0
	v_mov_b32_e32 v33, v0
	v_mov_b32_e32 v34, v0
	v_mov_b32_e32 v35, v0
	v_mov_b32_e32 v36, v0
	v_mov_b32_e32 v37, v0
	v_mov_b32_e32 v38, v0
	v_mov_b32_e32 v39, v0
	v_mov_b32_e32 v48, v0
	v_mov_b32_e32 v49, v0
	v_mov_b32_e32 v50, v0
	v_mov_b32_e32 v51, v0
	v_mov_b32_e32 v52, v0
	v_mov_b32_e32 v53, v0
	v_mov_b32_e32 v54, v0
	v_mov_b32_e32 v55, v0
	v_mov_b32_e32 v8, v0
	v_mov_b32_e32 v9, v0
	v_mov_b32_e32 v10, v0
	v_mov_b32_e32 v11, v0
	v_mov_b32_e32 v12, v0
	v_mov_b32_e32 v13, v0
	v_mov_b32_e32 v14, v0
	v_mov_b32_e32 v15, v0
	v_mov_b32_e32 v24, v0
	v_mov_b32_e32 v25, v0
	v_mov_b32_e32 v26, v0
	v_mov_b32_e32 v27, v0
	v_mov_b32_e32 v28, v0
	v_mov_b32_e32 v29, v0
	v_mov_b32_e32 v30, v0
	v_mov_b32_e32 v31, v0
	v_mov_b32_e32 v40, v0
	v_mov_b32_e32 v41, v0
	v_mov_b32_e32 v42, v0
	v_mov_b32_e32 v43, v0
	v_mov_b32_e32 v44, v0
	v_mov_b32_e32 v45, v0
	v_mov_b32_e32 v46, v0
	v_mov_b32_e32 v47, v0
	v_mov_b32_e32 v56, v0
	v_mov_b32_e32 v57, v0
	v_mov_b32_e32 v58, v0
	v_mov_b32_e32 v59, v0
	v_mov_b32_e32 v60, v0
	v_mov_b32_e32 v61, v0
	v_mov_b32_e32 v62, v0
	v_mov_b32_e32 v63, v0
	v_mov_b32_e32 v64, v0
	v_mov_b32_e32 v65, v0
	v_mov_b32_e32 v66, v0
	v_mov_b32_e32 v67, v0
	v_mov_b32_e32 v68, v0
	v_mov_b32_e32 v69, v0
	v_mov_b32_e32 v70, v0
	v_mov_b32_e32 v71, v0
	v_mov_b32_e32 v80, v0
	v_mov_b32_e32 v81, v0
	v_mov_b32_e32 v82, v0
	v_mov_b32_e32 v83, v0
	v_mov_b32_e32 v84, v0
	v_mov_b32_e32 v85, v0
	v_mov_b32_e32 v86, v0
	v_mov_b32_e32 v87, v0
	v_mov_b32_e32 v96, v0
	v_mov_b32_e32 v97, v0
	v_mov_b32_e32 v98, v0
	v_mov_b32_e32 v99, v0
	v_mov_b32_e32 v100, v0
	v_mov_b32_e32 v101, v0
	v_mov_b32_e32 v102, v0
	v_mov_b32_e32 v103, v0
	v_mov_b32_e32 v112, v0
	v_mov_b32_e32 v113, v0
	v_mov_b32_e32 v114, v0
	v_mov_b32_e32 v115, v0
	v_mov_b32_e32 v116, v0
	v_mov_b32_e32 v117, v0
	v_mov_b32_e32 v118, v0
	v_mov_b32_e32 v119, v0
	v_mov_b32_e32 v72, v0
	v_mov_b32_e32 v73, v0
	v_mov_b32_e32 v74, v0
	v_mov_b32_e32 v75, v0
	v_mov_b32_e32 v76, v0
	v_mov_b32_e32 v77, v0
	v_mov_b32_e32 v78, v0
	v_mov_b32_e32 v79, v0
	v_mov_b32_e32 v88, v0
	v_mov_b32_e32 v89, v0
	v_mov_b32_e32 v90, v0
	v_mov_b32_e32 v91, v0
	v_mov_b32_e32 v92, v0
	v_mov_b32_e32 v93, v0
	v_mov_b32_e32 v94, v0
	v_mov_b32_e32 v95, v0
	v_mov_b32_e32 v104, v0
	v_mov_b32_e32 v105, v0
	v_mov_b32_e32 v106, v0
	v_mov_b32_e32 v107, v0
	v_mov_b32_e32 v108, v0
	v_mov_b32_e32 v109, v0
	v_mov_b32_e32 v110, v0
	v_mov_b32_e32 v111, v0
	v_mov_b32_e32 v120, v0
	v_mov_b32_e32 v121, v0
	v_mov_b32_e32 v122, v0
	v_mov_b32_e32 v123, v0
	v_mov_b32_e32 v124, v0
	v_mov_b32_e32 v125, v0
	v_mov_b32_e32 v126, v0
	v_mov_b32_e32 v127, v0
	v_add_u32_e32 v230, 0x18000, v210
	v_add_u32_e32 v231, 0x1c000, v210
.LBB0_1410:
	ds_read_b128 v[128:131], v211
	ds_read_b128 v[132:135], v211 offset:1024
	ds_read_b128 v[136:139], v211 offset:2048
	ds_read_b128 v[140:143], v211 offset:3072
	ds_read_b128 v[144:147], v212
	ds_read_b128 v[148:151], v212 offset:1024
	ds_read_b128 v[152:155], v212 offset:2048
	ds_read_b128 v[156:159], v212 offset:3072
	s_add_u32 s45, s50, 0xffc00080
	s_addc_u32 s52, s51, -1
	s_cmp_eq_u32 s85, s43
	s_cselect_b32 s55, s47, s52
	s_cselect_b32 s54, s46, s45
	s_cselect_b32 s53, s49, s41
	s_cselect_b32 s52, s48, s7
	s_add_i32 m0, s9, 0xc000
	ds_read_b128 v[160:163], v213
	ds_read_b128 v[164:167], v213 offset:1024
	ds_read_b128 v[168:171], v213 offset:2048
	ds_read_b128 v[172:175], v213 offset:3072
	ds_read_b128 v[176:179], v213 offset:4096
	ds_read_b128 v[180:183], v213 offset:5120
	ds_read_b128 v[196:199], v213 offset:6144
	ds_read_b128 v[200:203], v213 offset:7168
	global_load_lds_dwordx4 v192, s[50:51]
	s_add_i32 m0, s9, 0xe000
	s_nop 0
	global_load_lds_dwordx4 v194, s[50:51]
	s_waitcnt vmcnt(8)
	s_waitcnt lgkmcnt(0)
	s_barrier
	v_mfma_f32_16x16x32_bf16 v[124:127], v[128:131], v[160:163], v[124:127]
	v_mfma_f32_16x16x32_bf16 v[124:127], v[132:135], v[164:167], v[124:127]
	v_mfma_f32_16x16x32_bf16 v[120:123], v[140:143], v[164:167], v[120:123]
	v_mfma_f32_16x16x32_bf16 v[120:123], v[136:139], v[160:163], v[120:123]
	v_mfma_f32_16x16x32_bf16 v[104:107], v[136:139], v[168:171], v[104:107]
	v_mfma_f32_16x16x32_bf16 v[104:107], v[140:143], v[172:175], v[104:107]
	v_mfma_f32_16x16x32_bf16 v[108:111], v[132:135], v[172:175], v[108:111]
	v_mfma_f32_16x16x32_bf16 v[108:111], v[128:131], v[168:171], v[108:111]
	v_mfma_f32_16x16x32_bf16 v[92:95], v[128:131], v[176:179], v[92:95]
	v_mfma_f32_16x16x32_bf16 v[92:95], v[132:135], v[180:183], v[92:95]
	v_mfma_f32_16x16x32_bf16 v[88:91], v[140:143], v[180:183], v[88:91]
	v_mfma_f32_16x16x32_bf16 v[88:91], v[136:139], v[176:179], v[88:91]
	v_mfma_f32_16x16x32_bf16 v[72:75], v[136:139], v[196:199], v[72:75]
	v_mfma_f32_16x16x32_bf16 v[72:75], v[140:143], v[200:203], v[72:75]
	v_mfma_f32_16x16x32_bf16 v[76:79], v[132:135], v[200:203], v[76:79]
	v_mfma_f32_16x16x32_bf16 v[76:79], v[128:131], v[196:199], v[76:79]
	v_mfma_f32_16x16x32_bf16 v[116:119], v[144:147], v[160:163], v[116:119]
	v_mfma_f32_16x16x32_bf16 v[116:119], v[148:151], v[164:167], v[116:119]
	v_mfma_f32_16x16x32_bf16 v[112:115], v[156:159], v[164:167], v[112:115]
	v_mfma_f32_16x16x32_bf16 v[112:115], v[152:155], v[160:163], v[112:115]
	v_mfma_f32_16x16x32_bf16 v[96:99], v[152:155], v[168:171], v[96:99]
	v_mfma_f32_16x16x32_bf16 v[96:99], v[156:159], v[172:175], v[96:99]
	v_mfma_f32_16x16x32_bf16 v[100:103], v[148:151], v[172:175], v[100:103]
	v_mfma_f32_16x16x32_bf16 v[100:103], v[144:147], v[168:171], v[100:103]
	v_mfma_f32_16x16x32_bf16 v[84:87], v[144:147], v[176:179], v[84:87]
	v_mfma_f32_16x16x32_bf16 v[84:87], v[148:151], v[180:183], v[84:87]
	v_mfma_f32_16x16x32_bf16 v[80:83], v[156:159], v[180:183], v[80:83]
	v_mfma_f32_16x16x32_bf16 v[80:83], v[152:155], v[176:179], v[80:83]
	v_mfma_f32_16x16x32_bf16 v[64:67], v[152:155], v[196:199], v[64:67]
	v_mfma_f32_16x16x32_bf16 v[64:67], v[156:159], v[200:203], v[64:67]
	v_mfma_f32_16x16x32_bf16 v[68:71], v[148:151], v[200:203], v[68:71]
	v_mfma_f32_16x16x32_bf16 v[68:71], v[144:147], v[196:199], v[68:71]
	s_barrier
; #define PG8_STAGE(bufoff, gbase, voff) do { _Pragma("unroll") for (int _i = 0; _i < 2; ++_i) \
;         __builtin_amdgcn_global_load_lds((const unsigned*)((const char*)(gbase) + (voff)[_i]), (PG8_LAS unsigned*)(lds + (bufoff) + ldsw + _i * 8192), 16, 0, 0); } while (0)
; #define PG8_LDA(dst, b, h) do { _Pragma("unroll") for (int m = 0; m < 4; ++m) _Pragma("unroll") for (int k = 0; k < 2; ++k) dst[m][k] = *(const PG8_LAS bf16x8*)(lds + PG8_SA(b, h) + aoff + m * 2048 + k * 1024); } while (0)
; #define PG8_LDB(dst, b, h) do { _Pragma("unroll") for (int n = 0; n < 2; ++n) _Pragma("unroll") for (int k = 0; k < 2; ++k) dst[n][k] = *(const PG8_LAS bf16x8*)(lds + PG8_SB(b, h) + boff + n * 2048 + k * 1024); } while (0)
; #define PG8_MMA(ai, bj, At, Bt) do { __builtin_amdgcn_s_setprio(1); _Pragma("unroll") for (int m = 0; m < 4; ++m) _Pragma("unroll") for (int n = 0; n < 2; ++n) _Pragma("unroll") for (int k = 0; k < 2; ++k) \
;         acc[ai][bj][m][n] = __builtin_amdgcn_mfma_f32_16x16x32_bf16(Bt[n][k], At[m][k], acc[ai][bj][m][n], 0, 0, 0); __builtin_amdgcn_s_setprio(0); } while (0)
; #define PG8_WAIT_V(n) asm volatile("s_waitcnt vmcnt(" #n ")" ::: "memory")
; #define PG8_WAIT_L(n) asm volatile("s_waitcnt lgkmcnt(" #n ")" ::: "memory")
; #define PG8_BAR __builtin_amdgcn_s_barrier()
; #define PG8_SCHED __builtin_amdgcn_sched_barrier(0)
; template <class Epi, class Sched, bool ALIGN_EPI = false, bool SP2 = false>
; __device__ __forceinline__ void gemm_phase(PG8_LAS unsigned char* lds, const Gemm g, const Sched& S, const Epi& E, int wave_s) {
;     ...
;             PG8_LDA(At, 0, 1); PG8_STAGE(PG8_SB(0, 0), b2, voffB); PG8_STAGE(PG8_SB(0, 1), b2 + hstep, voffB); PG8_STAGE(PG8_SA(0, 0), a2, voffA);
;             PG8_WAIT_V(8); PG8_WAIT_L(0); PG8_BAR; PG8_MMA(1, 0, At, B0); PG8_MMA(1, 1, At, B1); PG8_BAR; PG8_SCHED;
;             PG8_LDB(B0, 1, 0); PG8_LDB(B1, 1, 1); PG8_SCHED; PG8_LDA(At, 1, 0); PG8_STAGE(PG8_SA(0, 1), a2 + hstep, voffA);
;             PG8_WAIT_V(8); PG8_WAIT_L(0); PG8_BAR; PG8_MMA(0, 0, At, B0); PG8_MMA(0, 1, At, B1); PG8_BAR; PG8_SCHED;
	s_add_i32 s45, s75, s60
	s_mov_b32 m0, s45
	ds_read_b128 v[160:163], v213 offset:16384
	ds_read_b128 v[164:167], v213 offset:17408
	ds_read_b128 v[168:171], v213 offset:18432
	ds_read_b128 v[172:175], v213 offset:19456
	ds_read_b128 v[176:179], v213 offset:20480
	ds_read_b128 v[180:183], v213 offset:21504
	ds_read_b128 v[196:199], v213 offset:22528
	ds_read_b128 v[200:203], v213 offset:23552
	global_load_lds_dwordx4 v186, s[52:53]
	s_add_i32 m0, s45, 0x2000
	s_add_u32 s86, s52, 0x400000
	s_addc_u32 s87, s53, 0
	s_add_i32 s45, s76, s60
	global_load_lds_dwordx4 v190, s[52:53]
	s_mov_b32 m0, s45
	s_nop 0
	global_load_lds_dwordx4 v186, s[86:87]
	s_add_i32 m0, s45, 0x2000
	s_nop 0
	global_load_lds_dwordx4 v190, s[86:87]
	s_mov_b32 m0, s9
	s_nop 0
	global_load_lds_dwordx4 v184, s[54:55]
	s_mov_b32 m0, s61
	s_nop 0
	global_load_lds_dwordx4 v188, s[54:55]
	s_waitcnt vmcnt(8)
	s_waitcnt lgkmcnt(0)
	s_barrier
	v_mfma_f32_16x16x32_bf16 v[60:63], v[128:131], v[160:163], v[60:63]
	v_mfma_f32_16x16x32_bf16 v[60:63], v[132:135], v[164:167], v[60:63]
	v_mfma_f32_16x16x32_bf16 v[56:59], v[140:143], v[164:167], v[56:59]
	v_mfma_f32_16x16x32_bf16 v[56:59], v[136:139], v[160:163], v[56:59]
	v_mfma_f32_16x16x32_bf16 v[40:43], v[136:139], v[168:171], v[40:43]
	v_mfma_f32_16x16x32_bf16 v[40:43], v[140:143], v[172:175], v[40:43]
	v_mfma_f32_16x16x32_bf16 v[44:47], v[132:135], v[172:175], v[44:47]
	v_mfma_f32_16x16x32_bf16 v[44:47], v[128:131], v[168:171], v[44:47]
	v_mfma_f32_16x16x32_bf16 v[28:31], v[128:131], v[176:179], v[28:31]
	v_mfma_f32_16x16x32_bf16 v[28:31], v[132:135], v[180:183], v[28:31]
	v_mfma_f32_16x16x32_bf16 v[24:27], v[140:143], v[180:183], v[24:27]
	v_mfma_f32_16x16x32_bf16 v[24:27], v[136:139], v[176:179], v[24:27]
	v_mfma_f32_16x16x32_bf16 v[8:11], v[136:139], v[196:199], v[8:11]
	v_mfma_f32_16x16x32_bf16 v[8:11], v[140:143], v[200:203], v[8:11]
	v_mfma_f32_16x16x32_bf16 v[12:15], v[132:135], v[200:203], v[12:15]
	v_mfma_f32_16x16x32_bf16 v[12:15], v[128:131], v[196:199], v[12:15]
	v_mfma_f32_16x16x32_bf16 v[52:55], v[144:147], v[160:163], v[52:55]
	v_mfma_f32_16x16x32_bf16 v[52:55], v[148:151], v[164:167], v[52:55]
	v_mfma_f32_16x16x32_bf16 v[48:51], v[156:159], v[164:167], v[48:51]
	v_mfma_f32_16x16x32_bf16 v[48:51], v[152:155], v[160:163], v[48:51]
	v_mfma_f32_16x16x32_bf16 v[32:35], v[152:155], v[168:171], v[32:35]
	v_mfma_f32_16x16x32_bf16 v[32:35], v[156:159], v[172:175], v[32:35]
	v_mfma_f32_16x16x32_bf16 v[36:39], v[148:151], v[172:175], v[36:39]
	v_mfma_f32_16x16x32_bf16 v[36:39], v[144:147], v[168:171], v[36:39]
	v_mfma_f32_16x16x32_bf16 v[20:23], v[144:147], v[176:179], v[20:23]
	v_mfma_f32_16x16x32_bf16 v[20:23], v[148:151], v[180:183], v[20:23]
	v_mfma_f32_16x16x32_bf16 v[16:19], v[156:159], v[180:183], v[16:19]
	v_mfma_f32_16x16x32_bf16 v[16:19], v[152:155], v[176:179], v[16:19]
	v_mfma_f32_16x16x32_bf16 v[0:3], v[152:155], v[196:199], v[0:3]
	v_mfma_f32_16x16x32_bf16 v[0:3], v[156:159], v[200:203], v[0:3]
	v_mfma_f32_16x16x32_bf16 v[4:7], v[148:151], v[200:203], v[4:7]
	v_mfma_f32_16x16x32_bf16 v[4:7], v[144:147], v[196:199], v[4:7]
	s_barrier
	s_add_i32 s45, 0, 0x18000
	s_add_i32 s86, 0, 0x1c000
	ds_read_b128 v[128:131], v230
	ds_read_b128 v[132:135], v230 offset:1024
	ds_read_b128 v[136:139], v230 offset:2048
	ds_read_b128 v[140:143], v230 offset:3072
	ds_read_b128 v[144:147], v231
	ds_read_b128 v[148:151], v231 offset:1024
	ds_read_b128 v[152:155], v231 offset:2048
	ds_read_b128 v[156:159], v231 offset:3072
	s_add_u32 s54, s54, 0x400000
	s_addc_u32 s55, s55, 0
	s_mov_b32 m0, s62
	s_nop 0
	ds_read_b128 v[160:163], v213 offset:32768
	ds_read_b128 v[164:167], v213 offset:33792
	ds_read_b128 v[168:171], v213 offset:34816
	ds_read_b128 v[172:175], v213 offset:35840
	ds_read_b128 v[176:179], v213 offset:36864
	ds_read_b128 v[180:183], v213 offset:37888
	ds_read_b128 v[196:199], v213 offset:38912
	ds_read_b128 v[200:203], v213 offset:39936
	global_load_lds_dwordx4 v184, s[54:55]
	s_mov_b32 m0, s63
	s_nop 0
	global_load_lds_dwordx4 v188, s[54:55]
	s_waitcnt vmcnt(8)
	s_waitcnt lgkmcnt(0)
	s_barrier
; #define PG8_STAGE(bufoff, gbase, voff) do { _Pragma("unroll") for (int _i = 0; _i < 2; ++_i) \
;         __builtin_amdgcn_global_load_lds((const unsigned*)((const char*)(gbase) + (voff)[_i]), (PG8_LAS unsigned*)(lds + (bufoff) + ldsw + _i * 8192), 16, 0, 0); } while (0)
; #define PG8_LDA(dst, b, h) do { _Pragma("unroll") for (int m = 0; m < 4; ++m) _Pragma("unroll") for (int k = 0; k < 2; ++k) dst[m][k] = *(const PG8_LAS bf16x8*)(lds + PG8_SA(b, h) + aoff + m * 2048 + k * 1024); } while (0)
; #define PG8_MMA(ai, bj, At, Bt) do { __builtin_amdgcn_s_setprio(1); _Pragma("unroll") for (int m = 0; m < 4; ++m) _Pragma("unroll") for (int n = 0; n < 2; ++n) _Pragma("unroll") for (int k = 0; k < 2; ++k) \
;         acc[ai][bj][m][n] = __builtin_amdgcn_mfma_f32_16x16x32_bf16(Bt[n][k], At[m][k], acc[ai][bj][m][n], 0, 0, 0); __builtin_amdgcn_s_setprio(0); } while (0)
; #define PG8_WAIT_V(n) asm volatile("s_waitcnt vmcnt(" #n ")" ::: "memory")
; #define PG8_WAIT_L(n) asm volatile("s_waitcnt lgkmcnt(" #n ")" ::: "memory")
; #define PG8_BAR __builtin_amdgcn_s_barrier()
; #define PG8_SCHED __builtin_amdgcn_sched_barrier(0)
; template <class Epi, class Sched, bool ALIGN_EPI = false, bool SP2 = false>
; __device__ __forceinline__ void gemm_phase(PG8_LAS unsigned char* lds, const Gemm g, const Sched& S, const Epi& E, int wave_s) {
;     ...
;             PG8_WAIT_V(8); PG8_WAIT_L(0); PG8_BAR; PG8_MMA(0, 0, At, B0); PG8_MMA(0, 1, At, B1); PG8_BAR; PG8_SCHED;
;             PG8_LDA(At, 1, 1); PG8_STAGE(PG8_SB(1, 0), b3, voffB); PG8_STAGE(PG8_SB(1, 1), b3 + hstep, voffB); PG8_STAGE(PG8_SA(1, 0), a3, voffA);
;             PG8_WAIT_V(8); PG8_WAIT_L(0); PG8_BAR; PG8_MMA(1, 0, At, B0); PG8_MMA(1, 1, At, B1); PG8_BAR; PG8_SCHED;
	v_mfma_f32_16x16x32_bf16 v[124:127], v[128:131], v[160:163], v[124:127]
	v_mfma_f32_16x16x32_bf16 v[124:127], v[132:135], v[164:167], v[124:127]
	v_mfma_f32_16x16x32_bf16 v[120:123], v[140:143], v[164:167], v[120:123]
	v_mfma_f32_16x16x32_bf16 v[120:123], v[136:139], v[160:163], v[120:123]
	v_mfma_f32_16x16x32_bf16 v[104:107], v[136:139], v[168:171], v[104:107]
	v_mfma_f32_16x16x32_bf16 v[104:107], v[140:143], v[172:175], v[104:107]
	v_mfma_f32_16x16x32_bf16 v[108:111], v[132:135], v[172:175], v[108:111]
	v_mfma_f32_16x16x32_bf16 v[108:111], v[128:131], v[168:171], v[108:111]
	v_mfma_f32_16x16x32_bf16 v[92:95], v[128:131], v[176:179], v[92:95]
	v_mfma_f32_16x16x32_bf16 v[92:95], v[132:135], v[180:183], v[92:95]
	v_mfma_f32_16x16x32_bf16 v[88:91], v[140:143], v[180:183], v[88:91]
	v_mfma_f32_16x16x32_bf16 v[88:91], v[136:139], v[176:179], v[88:91]
	v_mfma_f32_16x16x32_bf16 v[72:75], v[136:139], v[196:199], v[72:75]
	v_mfma_f32_16x16x32_bf16 v[72:75], v[140:143], v[200:203], v[72:75]
	v_mfma_f32_16x16x32_bf16 v[76:79], v[132:135], v[200:203], v[76:79]
	v_mfma_f32_16x16x32_bf16 v[76:79], v[128:131], v[196:199], v[76:79]
	v_mfma_f32_16x16x32_bf16 v[116:119], v[144:147], v[160:163], v[116:119]
	v_mfma_f32_16x16x32_bf16 v[116:119], v[148:151], v[164:167], v[116:119]
	v_mfma_f32_16x16x32_bf16 v[112:115], v[156:159], v[164:167], v[112:115]
	v_mfma_f32_16x16x32_bf16 v[112:115], v[152:155], v[160:163], v[112:115]
	v_mfma_f32_16x16x32_bf16 v[96:99], v[152:155], v[168:171], v[96:99]
	v_mfma_f32_16x16x32_bf16 v[96:99], v[156:159], v[172:175], v[96:99]
	v_mfma_f32_16x16x32_bf16 v[100:103], v[148:151], v[172:175], v[100:103]
	v_mfma_f32_16x16x32_bf16 v[100:103], v[144:147], v[168:171], v[100:103]
	v_mfma_f32_16x16x32_bf16 v[84:87], v[144:147], v[176:179], v[84:87]
	v_mfma_f32_16x16x32_bf16 v[84:87], v[148:151], v[180:183], v[84:87]
	v_mfma_f32_16x16x32_bf16 v[80:83], v[156:159], v[180:183], v[80:83]
	v_mfma_f32_16x16x32_bf16 v[80:83], v[152:155], v[176:179], v[80:83]
	v_mfma_f32_16x16x32_bf16 v[64:67], v[152:155], v[196:199], v[64:67]
	v_mfma_f32_16x16x32_bf16 v[64:67], v[156:159], v[200:203], v[64:67]
	v_mfma_f32_16x16x32_bf16 v[68:71], v[148:151], v[200:203], v[68:71]
	v_mfma_f32_16x16x32_bf16 v[68:71], v[144:147], v[196:199], v[68:71]
	s_barrier
	s_add_i32 s45, s45, s60
	s_mov_b32 m0, s45
	ds_read_b128 v[160:163], v213 offset:49152
	ds_read_b128 v[164:167], v213 offset:50176
	ds_read_b128 v[168:171], v213 offset:51200
	ds_read_b128 v[172:175], v213 offset:52224
	ds_read_b128 v[176:179], v213 offset:53248
	ds_read_b128 v[180:183], v213 offset:54272
	ds_read_b128 v[196:199], v213 offset:55296
	ds_read_b128 v[200:203], v213 offset:56320
	s_add_u32 s94, s52, 0x80
	s_addc_u32 s95, s53, 0
	global_load_lds_dwordx4 v186, s[94:95]
	s_add_i32 m0, s45, 0x2000
	s_add_u32 s52, s52, 0x400080
	s_addc_u32 s53, s53, 0
	s_add_i32 s45, s86, s60
	global_load_lds_dwordx4 v190, s[94:95]
	s_mov_b32 m0, s45
	s_nop 0
	global_load_lds_dwordx4 v186, s[52:53]
	s_add_i32 m0, s45, 0x2000
	s_nop 0
	global_load_lds_dwordx4 v190, s[52:53]
	s_mov_b32 m0, s70
	s_nop 0
	s_add_u32 s96, s54, 0xffc00080
	s_addc_u32 s97, s55, -1
	global_load_lds_dwordx4 v184, s[96:97]
	s_mov_b32 m0, s71
	s_nop 0
	global_load_lds_dwordx4 v188, s[96:97]
	s_waitcnt vmcnt(8)
	s_waitcnt lgkmcnt(0)
	s_barrier
	v_mfma_f32_16x16x32_bf16 v[60:63], v[128:131], v[160:163], v[60:63]
	v_mfma_f32_16x16x32_bf16 v[60:63], v[132:135], v[164:167], v[60:63]
	v_mfma_f32_16x16x32_bf16 v[56:59], v[140:143], v[164:167], v[56:59]
	v_mfma_f32_16x16x32_bf16 v[56:59], v[136:139], v[160:163], v[56:59]
	v_mfma_f32_16x16x32_bf16 v[40:43], v[136:139], v[168:171], v[40:43]
	v_mfma_f32_16x16x32_bf16 v[40:43], v[140:143], v[172:175], v[40:43]
	v_mfma_f32_16x16x32_bf16 v[44:47], v[132:135], v[172:175], v[44:47]
	v_mfma_f32_16x16x32_bf16 v[44:47], v[128:131], v[168:171], v[44:47]
	v_mfma_f32_16x16x32_bf16 v[28:31], v[128:131], v[176:179], v[28:31]
	v_mfma_f32_16x16x32_bf16 v[28:31], v[132:135], v[180:183], v[28:31]
	v_mfma_f32_16x16x32_bf16 v[24:27], v[140:143], v[180:183], v[24:27]
	v_mfma_f32_16x16x32_bf16 v[24:27], v[136:139], v[176:179], v[24:27]
	v_mfma_f32_16x16x32_bf16 v[8:11], v[136:139], v[196:199], v[8:11]
	v_mfma_f32_16x16x32_bf16 v[8:11], v[140:143], v[200:203], v[8:11]
	v_mfma_f32_16x16x32_bf16 v[12:15], v[132:135], v[200:203], v[12:15]
	v_mfma_f32_16x16x32_bf16 v[12:15], v[128:131], v[196:199], v[12:15]
	v_mfma_f32_16x16x32_bf16 v[52:55], v[144:147], v[160:163], v[52:55]
	v_mfma_f32_16x16x32_bf16 v[52:55], v[148:151], v[164:167], v[52:55]
	v_mfma_f32_16x16x32_bf16 v[48:51], v[156:159], v[164:167], v[48:51]
	v_mfma_f32_16x16x32_bf16 v[48:51], v[152:155], v[160:163], v[48:51]
	v_mfma_f32_16x16x32_bf16 v[32:35], v[152:155], v[168:171], v[32:35]
	v_mfma_f32_16x16x32_bf16 v[32:35], v[156:159], v[172:175], v[32:35]
	v_mfma_f32_16x16x32_bf16 v[36:39], v[148:151], v[172:175], v[36:39]
	v_mfma_f32_16x16x32_bf16 v[36:39], v[144:147], v[168:171], v[36:39]
	v_mfma_f32_16x16x32_bf16 v[20:23], v[144:147], v[176:179], v[20:23]
	v_mfma_f32_16x16x32_bf16 v[20:23], v[148:151], v[180:183], v[20:23]
	v_mfma_f32_16x16x32_bf16 v[16:19], v[156:159], v[180:183], v[16:19]
	v_mfma_f32_16x16x32_bf16 v[16:19], v[152:155], v[176:179], v[16:19]
	v_mfma_f32_16x16x32_bf16 v[0:3], v[152:155], v[196:199], v[0:3]
	v_mfma_f32_16x16x32_bf16 v[0:3], v[156:159], v[200:203], v[0:3]
	v_mfma_f32_16x16x32_bf16 v[4:7], v[148:151], v[200:203], v[4:7]
	v_mfma_f32_16x16x32_bf16 v[4:7], v[144:147], v[196:199], v[4:7]
	s_barrier
	s_add_i32 s45, s43, 2
	s_add_u32 s50, s50, 0x100
	s_addc_u32 s51, s51, 0
	s_add_u32 s7, s7, 0x100
	s_addc_u32 s41, s41, 0
	s_cmp_ge_i32 s43, s85
	s_mov_b32 s43, s45
	s_cbranch_scc0 .LBB0_1410
	s_and_b64 vcc, exec, s[20:21]
	s_cbranch_vccz .LBB0_1413
	s_barrier
